# waitcnt placement: adjacent lgkmcnt(0) / vmcnt(0) waits at the MA row-load sites merged into one, on top of v37
# baseline (speedup 1.0000x reference)
; #define GAS __attribute__((address_space(1)))
; __device__ __forceinline__ void phase_ma(const Params& p, Frame& F, int l, const bool fd, const float* xin32) {
;     ...
;             for (int j = 0; j < 4; ++j) { if (!fd) { const v2u xw = *(const GAS v2u*)(xb + (size_t)row * D + 256 * j + 4 * F.lane); h[r][j] = (f32x4){bf_lo(xw.x), bf_hi(xw.x), bf_lo(xw.y), bf_hi(xw.y)}; } ss += (h[r][j].x * h[r][j].x + h[r][j].y * h[r][j].y) + (h[r][j].z * h[r][j].z + h[r][j].w * h[r][j].w); }
.LBB0_617:
	s_waitcnt vmcnt(0) lgkmcnt(0)
	v_lshlrev_b32_e32 v68, 16, v198
	v_and_b32_e32 v69, 0xffff0000, v198
	v_lshlrev_b32_e32 v96, 16, v199
	v_and_b32_e32 v97, 0xffff0000, v199
	s_and_b64 vcc, exec, s[48:49]
	s_cbranch_vccnz .LBB0_669
	s_branch .LBB0_668

; #define GAS __attribute__((address_space(1)))
; __device__ __forceinline__ void phase_ma(const Params& p, Frame& F, int l, const bool fd, const float* xin32) {
;     ...
;             for (int j = 0; j < 4; ++j) { if (!fd) { const v2u xw = *(const GAS v2u*)(xb + (size_t)row * D + 256 * j + 4 * F.lane); h[r][j] = (f32x4){bf_lo(xw.x), bf_hi(xw.x), bf_lo(xw.y), bf_hi(xw.y)}; } ss += (h[r][j].x * h[r][j].x + h[r][j].y * h[r][j].y) + (h[r][j].z * h[r][j].z + h[r][j].w * h[r][j].w); }
.LBB0_666:
	s_waitcnt vmcnt(0) lgkmcnt(0)
	v_lshlrev_b32_e32 v70, 16, v196
	v_and_b32_e32 v71, 0xffff0000, v196
	v_lshlrev_b32_e32 v104, 16, v197
	v_and_b32_e32 v105, 0xffff0000, v197
	s_and_b64 vcc, exec, s[48:49]
	s_cbranch_vccz .LBB0_617

; #define GAS __attribute__((address_space(1)))
; __device__ __forceinline__ void phase_ma(const Params& p, Frame& F, int l, const bool fd, const float* xin32) {
;     ...
;             for (int j = 0; j < 4; ++j) { if (!fd) { const v2u xw = *(const GAS v2u*)(xb + (size_t)row * D + 256 * j + 4 * F.lane); h[r][j] = (f32x4){bf_lo(xw.x), bf_hi(xw.x), bf_lo(xw.y), bf_hi(xw.y)}; } ss += (h[r][j].x * h[r][j].x + h[r][j].y * h[r][j].y) + (h[r][j].z * h[r][j].z + h[r][j].w * h[r][j].w); }
.LBB0_672:
	s_waitcnt vmcnt(0) lgkmcnt(0)
	v_lshlrev_b32_e32 v76, 16, v202
	v_and_b32_e32 v77, 0xffff0000, v202
	v_lshlrev_b32_e32 v110, 16, v203
	v_and_b32_e32 v111, 0xffff0000, v203
	s_and_b64 vcc, exec, s[48:49]
	s_cbranch_vccz .LBB0_723

; #define GAS __attribute__((address_space(1)))
; __device__ __forceinline__ void phase_ma(const Params& p, Frame& F, int l, const bool fd, const float* xin32) {
;     ...
;             for (int j = 0; j < 4; ++j) { if (!fd) { const v2u xw = *(const GAS v2u*)(xb + (size_t)row * D + 256 * j + 4 * F.lane); h[r][j] = (f32x4){bf_lo(xw.x), bf_hi(xw.x), bf_lo(xw.y), bf_hi(xw.y)}; } ss += (h[r][j].x * h[r][j].x + h[r][j].y * h[r][j].y) + (h[r][j].z * h[r][j].z + h[r][j].w * h[r][j].w); }
.LBB0_674:
	s_waitcnt vmcnt(0) lgkmcnt(0)
	v_lshlrev_b32_e32 v72, 16, v206
	v_and_b32_e32 v73, 0xffff0000, v206
	v_lshlrev_b32_e32 v92, 16, v207
	v_and_b32_e32 v93, 0xffff0000, v207
	s_and_b64 vcc, exec, s[48:49]
	s_cbranch_vccnz .LBB0_726
	s_branch .LBB0_725

; #define GAS __attribute__((address_space(1)))
; __device__ __forceinline__ void phase_ma(const Params& p, Frame& F, int l, const bool fd, const float* xin32) {
;     ...
;             for (int j = 0; j < 4; ++j) { if (!fd) { const v2u xw = *(const GAS v2u*)(xb + (size_t)row * D + 256 * j + 4 * F.lane); h[r][j] = (f32x4){bf_lo(xw.x), bf_hi(xw.x), bf_lo(xw.y), bf_hi(xw.y)}; } ss += (h[r][j].x * h[r][j].x + h[r][j].y * h[r][j].y) + (h[r][j].z * h[r][j].z + h[r][j].w * h[r][j].w); }
.LBB0_723:
	s_waitcnt vmcnt(0) lgkmcnt(0)
	v_lshlrev_b32_e32 v74, 16, v204
	v_and_b32_e32 v75, 0xffff0000, v204
	v_lshlrev_b32_e32 v102, 16, v205
	v_and_b32_e32 v103, 0xffff0000, v205
	s_and_b64 vcc, exec, s[48:49]
	s_cbranch_vccz .LBB0_674

; #define GAS __attribute__((address_space(1)))
; __device__ __forceinline__ void phase_ma(const Params& p, Frame& F, int l, const bool fd, const float* xin32) {
;     ...
;             for (int j = 0; j < 4; ++j) { if (!fd) { const v2u xw = *(const GAS v2u*)(xb + (size_t)row * D + 256 * j + 4 * F.lane); h[r][j] = (f32x4){bf_lo(xw.x), bf_hi(xw.x), bf_lo(xw.y), bf_hi(xw.y)}; } ss += (h[r][j].x * h[r][j].x + h[r][j].y * h[r][j].y) + (h[r][j].z * h[r][j].z + h[r][j].w * h[r][j].w); }
.LBB0_729:
	s_waitcnt vmcnt(0) lgkmcnt(0)
	v_lshlrev_b32_e32 v86, 16, v210
	v_and_b32_e32 v87, 0xffff0000, v210
	v_lshlrev_b32_e32 v116, 16, v211
	v_and_b32_e32 v117, 0xffff0000, v211
	s_and_b64 vcc, exec, s[48:49]
	s_cbranch_vccz .LBB0_780

; #define GAS __attribute__((address_space(1)))
; __device__ __forceinline__ void phase_ma(const Params& p, Frame& F, int l, const bool fd, const float* xin32) {
;     ...
;             for (int j = 0; j < 4; ++j) { if (!fd) { const v2u xw = *(const GAS v2u*)(xb + (size_t)row * D + 256 * j + 4 * F.lane); h[r][j] = (f32x4){bf_lo(xw.x), bf_hi(xw.x), bf_lo(xw.y), bf_hi(xw.y)}; } ss += (h[r][j].x * h[r][j].x + h[r][j].y * h[r][j].y) + (h[r][j].z * h[r][j].z + h[r][j].w * h[r][j].w); }
.LBB0_731:
	s_waitcnt vmcnt(0) lgkmcnt(0)
	v_lshlrev_b32_e32 v80, 16, v214
	v_and_b32_e32 v81, 0xffff0000, v214
	v_lshlrev_b32_e32 v100, 16, v215
	v_and_b32_e32 v101, 0xffff0000, v215
	s_and_b64 vcc, exec, s[48:49]
	s_cbranch_vccnz .LBB0_783
	s_branch .LBB0_782

; #define GAS __attribute__((address_space(1)))
; __device__ __forceinline__ void phase_ma(const Params& p, Frame& F, int l, const bool fd, const float* xin32) {
;     ...
;             for (int j = 0; j < 4; ++j) { if (!fd) { const v2u xw = *(const GAS v2u*)(xb + (size_t)row * D + 256 * j + 4 * F.lane); h[r][j] = (f32x4){bf_lo(xw.x), bf_hi(xw.x), bf_lo(xw.y), bf_hi(xw.y)}; } ss += (h[r][j].x * h[r][j].x + h[r][j].y * h[r][j].y) + (h[r][j].z * h[r][j].z + h[r][j].w * h[r][j].w); }
.LBB0_780:
	s_waitcnt vmcnt(0) lgkmcnt(0)
	v_lshlrev_b32_e32 v82, 16, v212
	v_and_b32_e32 v83, 0xffff0000, v212
	v_lshlrev_b32_e32 v106, 16, v213
	v_and_b32_e32 v107, 0xffff0000, v213
	s_and_b64 vcc, exec, s[48:49]
	s_cbranch_vccz .LBB0_731

; #define GAS __attribute__((address_space(1)))
; __device__ __forceinline__ void phase_ma(const Params& p, Frame& F, int l, const bool fd, const float* xin32) {
;     ...
;             for (int j = 0; j < 4; ++j) { if (!fd) { const v2u xw = *(const GAS v2u*)(xb + (size_t)row * D + 256 * j + 4 * F.lane); h[r][j] = (f32x4){bf_lo(xw.x), bf_hi(xw.x), bf_lo(xw.y), bf_hi(xw.y)}; } ss += (h[r][j].x * h[r][j].x + h[r][j].y * h[r][j].y) + (h[r][j].z * h[r][j].z + h[r][j].w * h[r][j].w); }
.LBB0_786:
	s_waitcnt vmcnt(0) lgkmcnt(0)
	v_lshlrev_b32_e32 v98, 16, v218
	v_and_b32_e32 v99, 0xffff0000, v218
	v_lshlrev_b32_e32 v120, 16, v219
	v_and_b32_e32 v121, 0xffff0000, v219
	s_and_b64 vcc, exec, s[48:49]
	s_cbranch_vccz .LBB0_837

; #define GAS __attribute__((address_space(1)))
; __device__ __forceinline__ void phase_ma(const Params& p, Frame& F, int l, const bool fd, const float* xin32) {
;     ...
;             for (int j = 0; j < 4; ++j) { if (!fd) { const v2u xw = *(const GAS v2u*)(xb + (size_t)row * D + 256 * j + 4 * F.lane); h[r][j] = (f32x4){bf_lo(xw.x), bf_hi(xw.x), bf_lo(xw.y), bf_hi(xw.y)}; } ss += (h[r][j].x * h[r][j].x + h[r][j].y * h[r][j].y) + (h[r][j].z * h[r][j].z + h[r][j].w * h[r][j].w); }
.LBB0_788:
	s_waitcnt vmcnt(0) lgkmcnt(0)
	v_lshlrev_b32_e32 v88, 16, v222
	v_and_b32_e32 v89, 0xffff0000, v222
	v_lshlrev_b32_e32 v108, 16, v223
	v_and_b32_e32 v109, 0xffff0000, v223
	s_and_b64 vcc, exec, s[48:49]
	s_cbranch_vccz .LBB0_839
	s_branch .LBB0_840

; #define GAS __attribute__((address_space(1)))
; __device__ __forceinline__ void phase_ma(const Params& p, Frame& F, int l, const bool fd, const float* xin32) {
;     ...
;             for (int j = 0; j < 4; ++j) { if (!fd) { const v2u xw = *(const GAS v2u*)(xb + (size_t)row * D + 256 * j + 4 * F.lane); h[r][j] = (f32x4){bf_lo(xw.x), bf_hi(xw.x), bf_lo(xw.y), bf_hi(xw.y)}; } ss += (h[r][j].x * h[r][j].x + h[r][j].y * h[r][j].y) + (h[r][j].z * h[r][j].z + h[r][j].w * h[r][j].w); }
.LBB0_837:
	s_waitcnt vmcnt(0) lgkmcnt(0)
	v_lshlrev_b32_e32 v90, 16, v220
	v_and_b32_e32 v91, 0xffff0000, v220
	v_lshlrev_b32_e32 v118, 16, v221
	v_and_b32_e32 v119, 0xffff0000, v221
	s_and_b64 vcc, exec, s[48:49]
	s_cbranch_vccz .LBB0_788
